# s_setprio 1 for waves 0-3 across the whole attention phase (prompt and sample units, epilogues), reset at phase end
# speedup vs baseline: 1.0018x; 1.0001x over previous
; __global__ void __launch_bounds__(NWAVES * 64, 2) mega_fwd(Args a) {
;     ...
;             { att::Tensors T{QB, KNA, KPEA, VTA, S1, UB, GBS, MG, a.in[6] + (size_t)l * 3 * DM, a.in[4] + ((size_t)l * NBATCH + g * GB) * 2 * DM};
; #pragma unroll 1
;               for (int i = vcu; i < 1280; i += G) {
;                   const int round = i >> 8, cu = i & 255, p = cu >> 1, odd = cu & 1, bl = p >> 3, h = p & 7;
;                   const int qb = odd ? (round == 0 ? 7 : round == 1 ? 5 : round == 2 ? 0 : -1) : (round == 0 ? 6 : round == 1 ? 4 : round == 2 ? 3 : round == 3 ? 2 : 1);
;                   if (qb >= 0) att::unit(lds, T, h, bl * SEQ + qb * 256, 8, false, 4 * qb, bl * SEQ, 0, 4 * qb + 4);
;                   else if (round == 3) att::unit(lds, T, h, TP + bl * DSEQ, 2, true, 32, TG + bl * PAST, TP + bl * DSEQ, 33);
;               } }
.LBB0_847:
	v_readlane_b32 s48, v254, 1
	v_readlane_b32 s54, v254, 7
	v_readlane_b32 s55, v254, 8
	v_readlane_b32 s2, v255, 37
	v_readlane_b32 s0, v255, 49
	s_mov_b64 s[42:43], s[88:89]
	s_mov_b64 s[6:7], s[54:55]
	s_cmpk_gt_i32 s47, 0x4ff
	v_readlane_b32 s49, v254, 2
	v_readlane_b32 s50, v254, 3
	v_readlane_b32 s51, v254, 4
	v_readlane_b32 s52, v254, 5
	v_readlane_b32 s53, v254, 6
	s_cbranch_scc1 .LBB0_955
	s_add_u32 s34, s42, 0x165a9000
	s_addc_u32 s35, s43, 0
	s_add_u32 s6, s42, 0x16dc9000
	s_addc_u32 s7, s43, 0
	s_add_u32 s64, s42, 0x1d0c9000
	s_addc_u32 s65, s43, 0
	s_add_u32 s66, s42, 0x252c9000
	v_readlane_b32 s48, v254, 13
	s_addc_u32 s67, s43, 0
	s_ashr_i32 s1, s0, 31
	s_mul_i32 s4, s0, 0x3000
	v_readlane_b32 s60, v254, 25
	s_mul_hi_i32 s3, s0, 0x3000
	v_readlane_b32 s61, v254, 26
	s_add_u32 s68, s60, s4
	s_addc_u32 s69, s61, s3
	s_lshl_b32 s2, s2, 4
	v_readlane_b32 s56, v254, 21
	s_ashr_i32 s3, s2, 31
	s_lshl_b64 s[0:1], s[0:1], 18
	v_readlane_b32 s57, v254, 22
	s_add_u32 s4, s56, s0
	s_addc_u32 s5, s57, s1
	s_lshl_b64 s[0:1], s[2:3], 13
	s_add_u32 s70, s4, s0
	s_addc_u32 s71, s5, s1
	s_add_u32 s72, s42, 0x316c9000
	s_addc_u32 s73, s43, 0
	s_add_u32 s74, s42, 0x252c9080
	s_addc_u32 s75, s43, 0
	v_readlane_b32 s49, v254, 14
	v_readlane_b32 s50, v254, 15
	v_readlane_b32 s51, v254, 16
	v_readlane_b32 s52, v254, 17
	v_readlane_b32 s53, v254, 18
	v_readlane_b32 s54, v254, 19
	v_readlane_b32 s55, v254, 20
	v_readlane_b32 s58, v254, 23
	v_readlane_b32 s59, v254, 24
	v_readlane_b32 s62, v254, 27
	v_readlane_b32 s63, v254, 28
	v_readfirstlane_b32 s0, v206
	s_nop 3
	s_cmp_ge_u32 s0, 0x100
	s_cbranch_scc1 .Lat_prio
	s_setprio 1
.Lat_prio:
	s_branch .LBB0_850
.LBB0_849:
	s_add_i32 s47, s47, s46
	v_readlane_b32 s28, v255, 43
	s_cmpk_lt_i32 s47, 0x500
	v_readlane_b32 s29, v255, 44
	s_cbranch_scc0 .LBB0_954

; __device__ __forceinline__ void xcd_barrier(const XcdBarrier& b) {
;     asm volatile("s_waitcnt vmcnt(0)" ::: "memory");
;     __syncthreads();
;     if (threadIdx.x == 0) {
;         unsigned* bar = b.bar;
;         __builtin_amdgcn_s_waitcnt(0);
;         unsigned nloc = b.st[0], nx = b.st[1];
;         if (nloc == 0u) { xcd_barrier_complete(bar, b.x, nloc, nx); b.st[0] = nloc; b.st[1] = nx; }
.LBB0_955:
	s_setprio 0
	v_readlane_b32 s0, v255, 46
	s_add_i32 s8, s0, 4
	s_cmp_lt_i32 s8, s91
	s_cselect_b64 s[22:23], -1, 0
	s_and_b64 s[0:1], s[30:31], s[22:23]
	s_andn2_b64 vcc, exec, s[0:1]
	s_cbranch_vccnz .LBB0_1009
	s_waitcnt vmcnt(0)
	s_waitcnt vmcnt(0) lgkmcnt(0)
	s_barrier
	s_mov_b64 s[6:7], exec
	v_readlane_b32 s0, v254, 45
	v_readlane_b32 s1, v254, 46
	s_and_b64 s[0:1], s[6:7], s[0:1]
	s_mov_b64 exec, s[0:1]
	s_cbranch_execz .LBB0_1008
	v_readlane_b32 s0, v255, 35
	s_waitcnt vmcnt(0) expcnt(0) lgkmcnt(0)
	s_nop 0
	v_mov_b32_e32 v0, s0
	ds_read_b32 v2, v0
	v_readlane_b32 s0, v255, 36
	s_waitcnt lgkmcnt(0)
	v_cmp_ne_u32_e32 vcc, 0, v2
	v_mov_b32_e32 v0, s0
	ds_read_b32 v0, v0
	s_cbranch_vccnz .LBB0_972
	s_mov_b32 s9, 1
	s_branch .LBB0_960
